# m15 + down-GEMM phases started in 4 workgroup groups 15 us apart so residual epilogues of different groups do not coincide
# baseline (speedup 1.0000x reference)
; #define PG8_STAGE(bufoff, gbase, voff) do { _Pragma("unroll") for (int _i = 0; _i < 2; ++_i) \
;         __builtin_amdgcn_global_load_lds((const unsigned*)((const char*)(gbase) + (voff)[_i]), (LAS unsigned*)(lds + (bufoff) + ldsw + _i * 8192), 16, 0, 0); } while (0)
; #define PG8_BAR __builtin_amdgcn_s_barrier()
; template <class Epi, class Sched, bool F8 = false>
; __device__ __forceinline__ void gemm_phase(LAS unsigned char* lds, const Gemm g, const Sched& S, const Epi& E) {
;     ...
;     const int wid = __builtin_amdgcn_readfirstlane(tid >> 6), lane = tid & 63, wr = wid >> 2, wc = wid & 3, fr = lane & 15, fq = lane >> 4;
;     using FragT = typename FragSel<F8>::type; constexpr int NKF = F8 ? 1 : 2;
;     unsigned sc1 = 0x7F7F7F7Fu; asm volatile("" : "+v"(sc1));
;     const int K = g.K, nt = K / BK;
;     unsigned voffA[2], voffB[2];
; #pragma unroll
;     for (int i = 0; i < 2; ++i) { int R, C; stage_rc(tid * 16 + i * 8192, R, C); const int Rb = (R & ~31) + perm32(R & 31);
;         voffA[i] = (unsigned)(R * K + C) * 2u; voffB[i] = (unsigned)(Rb * K + C) * 2u; }
;     asm volatile("" : "+v"(voffA[0]), "+v"(voffA[1]), "+v"(voffB[0]), "+v"(voffB[1]));
;     const size_t kstep = (size_t)(BK * 2);
;     const size_t hstep = (size_t)HALF * K * 2;
;     const size_t tstep = 2 * hstep;
;     const unsigned ldsw = (unsigned)wid * 1024u;
;     const int aoff = lds_byte(wr * 64 + fr, fq * 8), boff = lds_byte(wc * 32 + fr, fq * 8);
;     ...
;     Unit cur, nxt; int ui = 0;
;     if (!S.next(0, cur)) return;
;     f32x4 acc[2][2][4][2];
; #pragma unroll
;     for (int a = 0; a < 2; ++a)
; #pragma unroll
;         for (int b = 0; b < 2; ++b)
; #pragma unroll
;             for (int m = 0; m < 4; ++m)
; #pragma unroll
;                 for (int n = 0; n < 2; ++n) acc[a][b][m][n] = (f32x4){0.f, 0.f, 0.f, 0.f};
;     FragT At[4][NKF], B0[2][NKF], B1[2][NKF];
;     unsigned long long pfv[8];
;     const char* cA = (const char*)g.A + (size_t)cur.pm * tstep; const char* cB = (const char*)g.Bt + (size_t)cur.pn * tstep;
;     PG8_STAGE(PG8_SB(0, 0), cB, voffB); PG8_STAGE(PG8_SB(0, 1), cB + hstep, voffB); PG8_STAGE(PG8_SA(0, 0), cA, voffA); PG8_STAGE(PG8_SA(0, 1), cA + hstep, voffA);
;     if (wr == 1) PG8_BAR;
;     PG8_WAIT_V(2); PG8_BAR;
;     PG8_STAGE(PG8_SB(1, 0), cB + kstep, voffB); PG8_STAGE(PG8_SA(1, 0), cA + kstep, voffA); PG8_STAGE(PG8_SB(1, 1), cB + hstep + kstep, voffB);
.LBB0_300:
	s_lshr_b32 s10, s2, 3
	s_and_b32 s10, s10, 3
	s_mul_i32 s10, s10, 1500
	s_memrealtime s[12:13]
	s_waitcnt lgkmcnt(0)
	s_add_u32 s10, s12, s10
.Ldly_0:
	s_memrealtime s[12:13]
	s_waitcnt lgkmcnt(0)
	s_sub_u32 s11, s10, s12
	s_cmp_gt_i32 s11, 0
	s_cbranch_scc1 .Ldly_0
	v_mov_b32_e32 v4, v202
	s_mov_b32 s5, 0x1ffffe0
	v_bfe_i32 v2, v4, 27, 1
	v_lshlrev_b32_e32 v0, 4, v4
	v_lshrrev_b32_e32 v2, 22, v2
	v_add_u32_e32 v2, v0, v2
	v_and_b32_e32 v2, 0xfffffc00, v2
	v_sub_u32_e32 v2, v0, v2
	v_lshrrev_b32_e32 v3, 4, v2
	s_waitcnt lgkmcnt(0)
	v_ashrrev_i32_e32 v1, 31, v4
	v_bitop3_b32 v2, v3, v2, 32 bitop3:0x6c
	v_lshrrev_b32_e32 v1, 26, v1
	v_ashrrev_i32_e32 v5, 31, v2
	v_add_u32_e32 v1, v4, v1
	v_lshrrev_b32_e32 v5, 26, v5
	v_ashrrev_i32_e32 v1, 6, v1
	v_add_u32_e32 v5, v2, v5
	v_lshlrev_b32_e32 v3, 3, v1
	v_ashrrev_i32_e32 v6, 6, v5
	v_and_b32_e32 v5, 0xc0, v5
	v_and_b32_e32 v3, -16, v3
	v_lshlrev_b32_e32 v1, 5, v1
	v_sub_u32_e32 v2, v2, v5
	v_add_u32_e32 v3, v6, v3
	v_and_b32_e32 v1, 32, v1
	v_ashrrev_i16_sdwa v2, v209, sext(v2) dst_sel:DWORD dst_unused:UNUSED_PAD src0_sel:DWORD src1_sel:BYTE_0
	v_add_u32_sdwa v1, v1, sext(v2) dst_sel:DWORD dst_unused:UNUSED_PAD src0_sel:DWORD src1_sel:WORD_0
	v_lshlrev_b32_e32 v2, 1, v3
	v_lshrrev_b32_e32 v5, 2, v3
	v_and_b32_e32 v6, 3, v6
	v_and_b32_e32 v2, 24, v2
	v_and_b32_e32 v5, 4, v5
	v_and_or_b32 v6, v3, s5, v6
	v_or3_b32 v2, v6, v5, v2
	s_movk_i32 s11, 0x580
	v_mul_lo_u32 v3, v3, s11
	v_mul_lo_u32 v2, v2, s11
	v_add_u32_e32 v0, 0x2000, v0
	v_add_lshl_u32 v168, v1, v3, 1
	v_add_lshl_u32 v160, v2, v1, 1
	v_ashrrev_i32_e32 v1, 31, v0
	v_lshrrev_b32_e32 v1, 22, v1
	v_add_u32_e32 v1, v0, v1
	v_ashrrev_i32_e32 v1, 10, v1
	v_mul_i32_i24_e32 v2, 0x400, v1
	v_sub_u32_e32 v0, v0, v2
	v_lshrrev_b32_e32 v2, 4, v0
	v_bitop3_b32 v0, v2, v0, 32 bitop3:0x6c
	v_ashrrev_i32_e32 v3, 31, v0
	v_lshrrev_b32_e32 v3, 26, v3
	v_add_u32_e32 v3, v0, v3
	v_lshlrev_b32_e32 v2, 3, v1
	v_ashrrev_i32_e32 v5, 6, v3
	v_and_b32_e32 v3, 0xc0, v3
	v_and_b32_e32 v2, -16, v2
	v_lshlrev_b32_e32 v1, 5, v1
	v_sub_u32_e32 v0, v0, v3
	v_add_u32_e32 v2, v5, v2
	v_and_b32_e32 v1, 32, v1
	v_ashrrev_i16_sdwa v0, v209, sext(v0) dst_sel:DWORD dst_unused:UNUSED_PAD src0_sel:DWORD src1_sel:BYTE_0
	v_add_u32_sdwa v0, v1, sext(v0) dst_sel:DWORD dst_unused:UNUSED_PAD src0_sel:DWORD src1_sel:WORD_0
	v_lshlrev_b32_e32 v1, 1, v2
	v_lshrrev_b32_e32 v3, 2, v2
	v_and_b32_e32 v5, 3, v5
	v_and_b32_e32 v1, 24, v1
	v_and_b32_e32 v3, 4, v3
	v_and_or_b32 v5, v2, s5, v5
	v_or3_b32 v1, v5, v3, v1
	v_readlane_b32 s12, v254, 19
	v_mul_lo_u32 v2, v2, s11
	v_mul_lo_u32 v1, v1, s11
	v_readlane_b32 s13, v254, 20
	v_readfirstlane_b32 s10, v4
	v_mov_b32_e32 v182, 0x7f7f7f7f
	v_add_lshl_u32 v170, v0, v2, 1
	v_add_lshl_u32 v172, v1, v0, 1
	s_andn2_b64 vcc, exec, s[12:13]
	s_cbranch_vccnz .LBB0_368
	s_and_b64 s[12:13], s[16:17], exec
	s_mov_b32 s5, 0x3a180000
	s_cselect_b32 s5, s5, 0x3a440000
	s_add_u32 s5, s28, s5
	s_addc_u32 s62, s29, 0
	s_ashr_i32 s11, s10, 6
	v_readlane_b32 s14, v254, 51
	s_ashr_i32 s12, s10, 8
	s_lshl_b32 s63, s11, 10
	s_mul_i32 s13, s14, 0xb0000
	s_add_u32 s36, s5, s13
	s_mul_hi_i32 s13, s14, 0xb0000
	s_addc_u32 s37, s62, s13
	s_add_i32 s74, s63, 0
	s_add_i32 m0, s74, 0x10000
	v_mov_b32_e32 v173, v161
	global_load_lds_dwordx4 v160, s[36:37]
	s_add_i32 m0, s74, 0x12000
	s_add_u32 s14, s36, 0x58000
	global_load_lds_dwordx4 v172, s[36:37]
	s_addc_u32 s15, s37, 0
	s_add_i32 m0, s74, 0x14000
	s_add_i32 s75, s74, 0x2000
	global_load_lds_dwordx4 v160, s[14:15]
	s_add_i32 m0, s74, 0x16000
	s_add_i32 s76, s74, 0x4000
	global_load_lds_dwordx4 v172, s[14:15]
	v_readlane_b32 s14, v255, 2
	s_mov_b32 m0, s74
	v_readlane_b32 s15, v255, 3
	s_add_i32 s77, s74, 0x6000
	s_cmp_eq_u32 s12, 1
	v_lshl_add_u64 v[0:1], s[36:37], 0, v[160:161]
	s_cselect_b64 s[18:19], -1, 0
	s_cmp_lg_u32 s12, 1
	global_load_lds_dwordx4 v168, s[14:15]
	s_mov_b32 m0, s75
	v_lshl_add_u64 v[2:3], s[36:37], 0, v[172:173]
	global_load_lds_dwordx4 v170, s[14:15]
	v_readlane_b32 s14, v255, 4
	s_mov_b32 m0, s76
	v_readlane_b32 s15, v255, 5
	s_nop 4
	global_load_lds_dwordx4 v168, s[14:15]
	s_mov_b32 m0, s77
	s_nop 0
	global_load_lds_dwordx4 v170, s[14:15]
	s_cbranch_scc1 .LBB0_303
	s_barrier
